# attention loop: MFMA / LDS / VMEM instructions kept on 8-byte boundaries by encoding the interleaved 4-byte VALU ops as VOP3 (same operations), loop head 8-byte aligned
# speedup vs baseline: 1.0070x; 1.0041x over previous
; #define MFMA(a, b, c) __builtin_amdgcn_mfma_f32_32x32x16_bf16((a), (b), (c), 0, 0, 0)
; DI void attn_item(const P& p, int l, int item, char* smem) {
;     ...
;     if (kt >= 0) {
;       const u16* Kc = Ks + (kt & 1) * (256 * 72);
;       const u16* Vc = Kc + 2 * 64 * 72;
;       bf16x8 kf[8];
; #pragma unroll
;       for (int i = 0; i < 8; ++i)
;         kf[i] = *(const bf16x8*)(Kc + (c * 64 + 32 * (i & 1) + li) * 72 + 16 * (i >> 1) + 8 * g);
;       u32x4 vf[16];
; #pragma unroll
;       for (int i = 0; i < 16; ++i) {
;         const int eb = i & 3, s = (i >> 2) & 1, kb = i >> 3;
;         vf[i] = *(const u32x4*)(Vc + (32 * eb + li) * 72 + 32 * kb + 16 * s + 8 * g);
;       }
;       f32x16 S[2];
; #pragma unroll
;       for (int kb = 0; kb < 2; ++kb)
; #pragma unroll
;         for (int r = 0; r < 16; ++r) S[kb][r] = negm;
; #pragma unroll
;       for (int i = 0; i < 8; ++i) S[i & 1] = MFMA(kf[i], qf[i >> 1], S[i & 1]);
;       u32x4 pk[4];
;       float sum = 0.f;
; #pragma unroll
;       for (int ch = 0; ch < 4; ++ch) {
;         const int kb = ch >> 1, s = ch & 1;
; #pragma unroll
;         for (int j2 = 0; j2 < 4; ++j2) {
;           const float p0 = __builtin_amdgcn_exp2f(S[kb][8 * s + 2 * j2]);
;           const float p1 = __builtin_amdgcn_exp2f(S[kb][8 * s + 2 * j2 + 1]);
;           sum += p0 + p1;
;           pk[ch][j2] = pack2(p0, p1);
;         }
;       }
;       ls += sum;
; #pragma unroll
;       for (int i = 0; i < 16; ++i) {
;         const int eb = i & 3, ch = i >> 2;
;         O[eb] = MFMA(__builtin_bit_cast(bf16x8, vf[i]), __builtin_bit_cast(bf16x8, pk[ch]), O[eb]);
;       }
.Lat_loop:
	s_waitcnt lgkmcnt(4)
	v_mfma_f32_32x32x16_bf16 v[64:79], v[136:139], v[176:179], v[64:79]
	ds_read_b128 v[136:139], v151 offset:9248
	v_exp_f32_e64 v104, v104
	v_exp_f32_e32 v105, v105
	v_mfma_f32_32x32x16_bf16 v[48:63], v[152:155], v[176:179], v[48:63]
	ds_read_b128 v[152:155], v151 offset:13856
	v_exp_f32_e64 v106, v106
	v_exp_f32_e32 v107, v107
	v_cvt_pk_bf16_f32 v180, v104, v105
	s_waitcnt lgkmcnt(4)
	v_mfma_f32_32x32x16_bf16 v[32:47], v[224:227], v[176:179], v[32:47]
	ds_read_b128 v[224:227], v151 offset:64
	v_exp_f32_e64 v108, v108
	v_exp_f32_e64 v109, v109
	v_cvt_pk_bf16_f32 v181, v106, v107
	v_mfma_f32_32x32x16_bf16 v[0:15], v[244:247], v[176:179], v[0:15]
	ds_read_b128 v[244:247], v151 offset:4672
	v_exp_f32_e64 v110, v110
	v_exp_f32_e64 v111, v111
	v_cvt_pk_bf16_f32 v182, v108, v109
	v_cvt_pk_bf16_f32 v183, v110, v111
	s_nop 0
	s_waitcnt lgkmcnt(4)
	v_mfma_f32_32x32x16_bf16 v[64:79], v[128:131], v[180:183], v[64:79]
	ds_read_b128 v[128:131], v151 offset:9280
	v_exp_f32_e64 v80, v80
	v_exp_f32_e64 v81, v81
	v_mfma_f32_32x32x16_bf16 v[48:63], v[132:135], v[180:183], v[48:63]
	ds_read_b128 v[132:135], v151 offset:13888
	v_exp_f32_e64 v82, v82
	v_exp_f32_e32 v83, v83
	v_cvt_pk_bf16_f32 v184, v80, v81
	s_waitcnt lgkmcnt(4)
	v_mfma_f32_32x32x16_bf16 v[32:47], v[136:139], v[180:183], v[32:47]
	ds_read_b128 v[136:139], v151 offset:96
	v_exp_f32_e64 v84, v84
	v_exp_f32_e64 v85, v85
	v_cvt_pk_bf16_f32 v185, v82, v83
	v_mfma_f32_32x32x16_bf16 v[0:15], v[152:155], v[180:183], v[0:15]
	ds_read_b128 v[152:155], v151 offset:4704
	v_exp_f32_e64 v86, v86
	v_exp_f32_e64 v87, v87
	v_cvt_pk_bf16_f32 v186, v84, v85
	v_cvt_pk_bf16_f32 v187, v86, v87
	s_nop 0
	s_waitcnt lgkmcnt(4)
	v_mfma_f32_32x32x16_bf16 v[64:79], v[224:227], v[184:187], v[64:79]
	ds_read_b128 v[224:227], v151 offset:9312
	v_exp_f32_e64 v88, v88
	v_exp_f32_e64 v89, v89
	v_mfma_f32_32x32x16_bf16 v[48:63], v[244:247], v[184:187], v[48:63]
	ds_read_b128 v[244:247], v151 offset:13920
	v_exp_f32_e64 v90, v90
	v_exp_f32_e32 v91, v91
	v_cvt_pk_bf16_f32 v192, v88, v89
	s_waitcnt lgkmcnt(4)
	v_mfma_f32_32x32x16_bf16 v[32:47], v[128:131], v[184:187], v[32:47]
	v_exp_f32_e64 v92, v92
	v_exp_f32_e32 v93, v93
	v_cvt_pk_bf16_f32 v193, v90, v91
	s_waitcnt vmcnt(0)
	ds_write_b128 v168, v[228:231] offset:36864
	ds_write_b128 v168, v[232:235] offset:46080
	v_mfma_f32_32x32x16_bf16 v[0:15], v[132:135], v[184:187], v[0:15]
	v_exp_f32_e64 v94, v94
	v_exp_f32_e32 v95, v95
	v_cvt_pk_bf16_f32 v194, v92, v93
	v_cvt_pk_bf16_f32 v195, v94, v95
	s_nop 0
	ds_write_b64 v169, v[236:237] offset:55296
	ds_write_b64 v169, v[238:239] offset:55312
	s_waitcnt lgkmcnt(6)
	v_mfma_f32_32x32x16_bf16 v[64:79], v[136:139], v[192:195], v[64:79]
	v_add_f32_e64 v167, v167, v104
	v_add_f32_e64 v190, v190, v105
	v_add_f32_e64 v191, v191, v106
	v_add_f32_e32 v196, v196, v107
	ds_write_b64 v143, v[240:241] offset:55296
	ds_write_b64 v143, v[242:243] offset:55312
	v_mfma_f32_32x32x16_bf16 v[48:63], v[152:155], v[192:195], v[48:63]
	v_add_f32_e64 v167, v167, v108
	v_add_f32_e64 v190, v190, v109
	v_add_f32_e64 v191, v191, v110
	v_add_f32_e32 v196, v196, v111
	s_waitcnt lgkmcnt(6)
	v_mfma_f32_32x32x16_bf16 v[32:47], v[224:227], v[192:195], v[32:47]
	v_add_f32_e64 v167, v167, v80
	v_add_f32_e64 v190, v190, v81
	v_add_f32_e64 v191, v191, v82
	v_add_f32_e64 v196, v196, v83
	v_mfma_f32_32x32x16_bf16 v[0:15], v[244:247], v[192:195], v[0:15]
	v_add_f32_e64 v167, v167, v84
	v_add_f32_e64 v190, v190, v85
	v_add_f32_e64 v191, v191, v86
	v_add_f32_e64 v196, v196, v87
	s_waitcnt lgkmcnt(0)
	s_barrier
	ds_read_b128 v[128:131], v150 offset:36864
	ds_read_b128 v[132:135], v150 offset:36896
	ds_read_b128 v[136:139], v150 offset:36928
	ds_read_b128 v[152:155], v150 offset:36960
	ds_read_b128 v[224:227], v150 offset:41472
	ds_read_b128 v[244:247], v150 offset:41504
	global_load_dwordx4 v[232:235], v[148:149], off
	global_load_dwordx4 v[228:231], v[156:157], off
	global_load_dwordx4 v[236:239], v[146:147], off
	global_load_dwordx4 v[240:243], v[144:145], off
	s_waitcnt lgkmcnt(4)
	v_mfma_f32_32x32x16_bf16 v[96:111], v[128:131], v[112:115], v[16:31]
	ds_read_b128 v[128:131], v150 offset:41536
	v_add_f32_e64 v167, v167, v88
	v_add_f32_e32 v190, v190, v89
	v_mfma_f32_32x32x16_bf16 v[96:111], v[132:135], v[116:119], v[96:111]
	ds_read_b128 v[132:135], v150 offset:41568
	v_add_f32_e64 v191, v191, v90
	v_add_f32_e32 v196, v196, v91
	s_waitcnt lgkmcnt(4)
	v_mfma_f32_32x32x16_bf16 v[96:111], v[136:139], v[124:127], v[96:111]
	ds_read_b128 v[136:139], v151 offset:36864
	v_add_f32_e64 v167, v167, v92
	v_add_f32_e64 v190, v190, v93
	v_mfma_f32_32x32x16_bf16 v[96:111], v[152:155], v[120:123], v[96:111]
	ds_read_b128 v[152:155], v151 offset:41472
	v_add_f32_e64 v191, v191, v94
	v_add_f32_e32 v196, v196, v95
	v_lshl_add_u64 v[148:149], v[148:149], 0, s[14:15]
	v_lshl_add_u64 v[156:157], v[156:157], 0, s[14:15]
	s_waitcnt lgkmcnt(4)
	v_mfma_f32_32x32x16_bf16 v[80:95], v[224:227], v[112:115], v[16:31]
	ds_read_b128 v[224:227], v151 offset:46080
	v_lshl_add_u64 v[146:147], v[146:147], 0, s[58:59]
	v_lshl_add_u64 v[144:145], v[144:145], 0, s[58:59]
	v_mfma_f32_32x32x16_bf16 v[80:95], v[244:247], v[116:119], v[80:95]
	ds_read_b128 v[244:247], v151 offset:50688
	s_nop 2
	v_exp_f32_e64 v96, v96
	v_exp_f32_e64 v97, v97
	s_waitcnt lgkmcnt(4)
; DI void attn_item(const P& p, int l, int item, char* smem) {
;     ...
;   for (int kt = -1; kt < 128; ++kt) {
;     if (kt + 1 < 128) {
;       u16* Kd = Ks + ((kt + 1) & 1) * (256 * 72);
;       u16* Vd = Kd + 2 * 64 * 72;
; #pragma unroll
;       for (int i = 0; i < 2; ++i) {
;         const int row = tid >> 3, kc = tid & 7;
;         *(u32x4*)(Kd + (i * 64 + row) * 72 + kc * 8) = kreg[i];
;       }
; #pragma unroll
;       for (int i = 0; i < 2; ++i) {
;         const int cid = tid + NT * i;
;         const int e = cid >> 3, kc = cid & 7;
;         uint2 w0; w0.x = vreg[i][0]; w0.y = vreg[i][1];
;         uint2 w1; w1.x = vreg[i][2]; w1.y = vreg[i][3];
;         u16* vd = Vd + e * 72 + (kc >> 1) * 16 + (kc & 1) * 4;
;         *(uint2*)vd = w0;
;         *(uint2*)(vd + 8) = w1;
;       }
;     }
;     if (kt + 2 < 128) {
;       const int kn = kt + 2;
; #pragma unroll
;       for (int i = 0; i < 2; ++i) kreg[i] = *(const u32x4*)(kbase + ((size_t)i * SEQ + kn * 64) * 64 + tid * 8);
; #pragma unroll
;       for (int i = 0; i < 2; ++i) {
;         const int cid = tid + NT * i;
;         const int e = cid >> 3, kc = cid & 7;
;         vreg[i] = *(const u32x4*)(vbase + (size_t)e * VTP + kn * 64 + kc * 8);
;       }
;     }
;     __builtin_amdgcn_sched_barrier(0x38F);
;     if (kt >= 0) {
;       const u16* Kc = Ks + (kt & 1) * (256 * 72);
;       const u16* Vc = Kc + 2 * 64 * 72;
;       bf16x8 kf[8];
; #pragma unroll
;       for (int i = 0; i < 8; ++i)
;         kf[i] = *(const bf16x8*)(Kc + (c * 64 + 32 * (i & 1) + li) * 72 + 16 * (i >> 1) + 8 * g);
;       u32x4 vf[16];
; #pragma unroll
;       for (int i = 0; i < 16; ++i) {
;         const int eb = i & 3, s = (i >> 2) & 1, kb = i >> 3;
;         vf[i] = *(const u32x4*)(Vc + (32 * eb + li) * 72 + 32 * kb + 16 * s + 8 * g);
;       }
;       f32x16 S[2];
; #pragma unroll
;       for (int kb = 0; kb < 2; ++kb)
; #pragma unroll
;         for (int r = 0; r < 16; ++r) S[kb][r] = negm;
; #pragma unroll
;       for (int i = 0; i < 8; ++i) S[i & 1] = MFMA(kf[i], qf[i >> 1], S[i & 1]);
;       u32x4 pk[4];
;       float sum = 0.f;
; #pragma unroll
;       for (int ch = 0; ch < 4; ++ch) {
;         const int kb = ch >> 1, s = ch & 1;
; #pragma unroll
;         for (int j2 = 0; j2 < 4; ++j2) {
;           const float p0 = __builtin_amdgcn_exp2f(S[kb][8 * s + 2 * j2]);
	v_mfma_f32_32x32x16_bf16 v[80:95], v[128:131], v[124:127], v[80:95]
	ds_read_b128 v[128:131], v151 offset:36896
	v_exp_f32_e64 v98, v98
	v_exp_f32_e64 v99, v99
	v_exp_f32_e64 v100, v100
	v_mfma_f32_32x32x16_bf16 v[80:95], v[132:135], v[120:123], v[80:95]
	ds_read_b128 v[132:135], v151 offset:41504
	v_exp_f32_e64 v101, v101
	v_exp_f32_e64 v102, v102
	v_exp_f32_e64 v103, v103
	v_add_f32_e64 v167, v167, v96
	v_add_f32_e64 v190, v190, v97
	v_add_f32_e64 v191, v191, v98
	v_cvt_pk_bf16_f32 v176, v96, v97
	v_cvt_pk_bf16_f32 v177, v98, v99
	v_cvt_pk_bf16_f32 v178, v100, v101
	v_cvt_pk_bf16_f32 v179, v102, v103
	v_add_f32_e64 v196, v196, v99
	v_add_f32_e64 v167, v167, v100
	v_add_f32_e64 v190, v190, v101
	v_add_f32_e64 v191, v191, v102
	v_add_f32_e32 v196, v196, v103
	s_waitcnt lgkmcnt(4)
	v_mfma_f32_32x32x16_bf16 v[64:79], v[136:139], v[176:179], v[64:79]
	ds_read_b128 v[136:139], v151 offset:46112
	v_exp_f32_e64 v104, v104
	v_exp_f32_e64 v105, v105
	v_mfma_f32_32x32x16_bf16 v[48:63], v[152:155], v[176:179], v[48:63]
	ds_read_b128 v[152:155], v151 offset:50720
	v_exp_f32_e64 v106, v106
	v_exp_f32_e32 v107, v107
	v_cvt_pk_bf16_f32 v180, v104, v105
	s_waitcnt lgkmcnt(4)
	v_mfma_f32_32x32x16_bf16 v[32:47], v[224:227], v[176:179], v[32:47]
	ds_read_b128 v[224:227], v151 offset:36928
	v_exp_f32_e64 v108, v108
	v_exp_f32_e64 v109, v109
	v_cvt_pk_bf16_f32 v181, v106, v107
	v_mfma_f32_32x32x16_bf16 v[0:15], v[244:247], v[176:179], v[0:15]
	ds_read_b128 v[244:247], v151 offset:41536
	v_exp_f32_e64 v110, v110
	v_exp_f32_e64 v111, v111
	v_cvt_pk_bf16_f32 v182, v108, v109
	v_cvt_pk_bf16_f32 v183, v110, v111
	s_nop 0
	s_waitcnt lgkmcnt(4)
	v_mfma_f32_32x32x16_bf16 v[64:79], v[128:131], v[180:183], v[64:79]
	ds_read_b128 v[128:131], v151 offset:46144
	v_exp_f32_e64 v80, v80
	v_exp_f32_e64 v81, v81
	v_mfma_f32_32x32x16_bf16 v[48:63], v[132:135], v[180:183], v[48:63]
	ds_read_b128 v[132:135], v151 offset:50752
	v_exp_f32_e64 v82, v82
	v_exp_f32_e32 v83, v83
	v_cvt_pk_bf16_f32 v184, v80, v81
	s_waitcnt lgkmcnt(4)
	v_mfma_f32_32x32x16_bf16 v[32:47], v[136:139], v[180:183], v[32:47]
	ds_read_b128 v[136:139], v151 offset:36960
	v_exp_f32_e64 v84, v84
	v_exp_f32_e64 v85, v85
	v_cvt_pk_bf16_f32 v185, v82, v83
	v_mfma_f32_32x32x16_bf16 v[0:15], v[152:155], v[180:183], v[0:15]
	ds_read_b128 v[152:155], v151 offset:41568
	v_exp_f32_e64 v86, v86
	v_exp_f32_e64 v87, v87
	v_cvt_pk_bf16_f32 v186, v84, v85
	v_cvt_pk_bf16_f32 v187, v86, v87
	s_nop 0
	s_waitcnt lgkmcnt(4)
	v_mfma_f32_32x32x16_bf16 v[64:79], v[224:227], v[184:187], v[64:79]
	ds_read_b128 v[224:227], v151 offset:46176
	v_exp_f32_e64 v88, v88
	v_exp_f32_e64 v89, v89
	v_mfma_f32_32x32x16_bf16 v[48:63], v[244:247], v[184:187], v[48:63]
	ds_read_b128 v[244:247], v151 offset:50784
	v_exp_f32_e64 v90, v90
	v_exp_f32_e32 v91, v91
	v_cvt_pk_bf16_f32 v192, v88, v89
	s_waitcnt lgkmcnt(4)
	v_mfma_f32_32x32x16_bf16 v[32:47], v[128:131], v[184:187], v[32:47]
	v_exp_f32_e64 v92, v92
	v_exp_f32_e32 v93, v93
	v_cvt_pk_bf16_f32 v193, v90, v91
	s_waitcnt vmcnt(0)
	ds_write_b128 v168, v[228:231] offset:0
	ds_write_b128 v168, v[232:235] offset:9216
	v_mfma_f32_32x32x16_bf16 v[0:15], v[132:135], v[184:187], v[0:15]
	v_exp_f32_e64 v94, v94
	v_exp_f32_e32 v95, v95
	v_cvt_pk_bf16_f32 v194, v92, v93
	v_cvt_pk_bf16_f32 v195, v94, v95
	s_nop 0
	ds_write_b64 v169, v[236:237] offset:18432
	ds_write_b64 v169, v[238:239] offset:18448
	s_waitcnt lgkmcnt(6)
	v_mfma_f32_32x32x16_bf16 v[64:79], v[136:139], v[192:195], v[64:79]
	v_add_f32_e64 v167, v167, v104
	v_add_f32_e64 v190, v190, v105
	v_add_f32_e64 v191, v191, v106
	v_add_f32_e32 v196, v196, v107
	ds_write_b64 v143, v[240:241] offset:18432
	ds_write_b64 v143, v[242:243] offset:18448
	v_mfma_f32_32x32x16_bf16 v[48:63], v[152:155], v[192:195], v[48:63]
	v_add_f32_e64 v167, v167, v108
	v_add_f32_e64 v190, v190, v109
	v_add_f32_e64 v191, v191, v110
	v_add_f32_e32 v196, v196, v111
	s_waitcnt lgkmcnt(6)
	v_mfma_f32_32x32x16_bf16 v[32:47], v[224:227], v[192:195], v[32:47]
	v_add_f32_e64 v167, v167, v80
	v_add_f32_e64 v190, v190, v81
	v_add_f32_e64 v191, v191, v82
	v_add_f32_e64 v196, v196, v83
	v_mfma_f32_32x32x16_bf16 v[0:15], v[244:247], v[192:195], v[0:15]
	v_add_f32_e64 v167, v167, v84
	v_add_f32_e64 v190, v190, v85
	v_add_f32_e64 v191, v191, v86
	v_add_f32_e32 v196, v196, v87
	s_waitcnt lgkmcnt(0)
	s_barrier
	s_add_i32 s10, s10, -1
	s_cmp_eq_u32 s10, 0
	s_cbranch_scc1 .Lat_exit
	ds_read_b128 v[128:131], v150 offset:0
	ds_read_b128 v[132:135], v150 offset:32
	ds_read_b128 v[136:139], v150 offset:64
	ds_read_b128 v[152:155], v150 offset:96
	ds_read_b128 v[224:227], v150 offset:4608
	ds_read_b128 v[244:247], v150 offset:4640
	global_load_dwordx4 v[232:235], v[148:149], off
	global_load_dwordx4 v[228:231], v[156:157], off
	global_load_dwordx4 v[236:239], v[146:147], off
	global_load_dwordx4 v[240:243], v[144:145], off
	s_waitcnt lgkmcnt(4)
	v_mfma_f32_32x32x16_bf16 v[96:111], v[128:131], v[112:115], v[16:31]
	ds_read_b128 v[128:131], v150 offset:4672
	v_add_f32_e64 v167, v167, v88
	v_add_f32_e32 v190, v190, v89
	v_mfma_f32_32x32x16_bf16 v[96:111], v[132:135], v[116:119], v[96:111]
	ds_read_b128 v[132:135], v150 offset:4704
	v_add_f32_e64 v191, v191, v90
	v_add_f32_e32 v196, v196, v91
	s_waitcnt lgkmcnt(4)
	v_mfma_f32_32x32x16_bf16 v[96:111], v[136:139], v[124:127], v[96:111]
	ds_read_b128 v[136:139], v151 offset:0
	v_add_f32_e64 v167, v167, v92
	v_add_f32_e64 v190, v190, v93
	v_mfma_f32_32x32x16_bf16 v[96:111], v[152:155], v[120:123], v[96:111]
	ds_read_b128 v[152:155], v151 offset:4608
	v_add_f32_e64 v191, v191, v94
	v_add_f32_e32 v196, v196, v95
	v_lshl_add_u64 v[148:149], v[148:149], 0, s[14:15]
	v_lshl_add_u64 v[156:157], v[156:157], 0, s[14:15]
	s_waitcnt lgkmcnt(4)
	v_mfma_f32_32x32x16_bf16 v[80:95], v[224:227], v[112:115], v[16:31]
	ds_read_b128 v[224:227], v151 offset:9216
	v_lshl_add_u64 v[146:147], v[146:147], 0, s[58:59]
	v_lshl_add_u64 v[144:145], v[144:145], 0, s[58:59]
	v_mfma_f32_32x32x16_bf16 v[80:95], v[244:247], v[116:119], v[80:95]
	ds_read_b128 v[244:247], v151 offset:13824
	s_nop 2
	v_exp_f32_e64 v96, v96
	v_exp_f32_e64 v97, v97
	s_waitcnt lgkmcnt(4)
	v_mfma_f32_32x32x16_bf16 v[80:95], v[128:131], v[124:127], v[80:95]
	ds_read_b128 v[128:131], v151 offset:32
	v_exp_f32_e64 v98, v98
	v_exp_f32_e64 v99, v99
	v_exp_f32_e64 v100, v100
	v_mfma_f32_32x32x16_bf16 v[80:95], v[132:135], v[120:123], v[80:95]
	ds_read_b128 v[132:135], v151 offset:4640
	v_exp_f32_e64 v101, v101
	v_exp_f32_e64 v102, v102
	v_exp_f32_e64 v103, v103
	v_add_f32_e64 v167, v167, v96
	v_add_f32_e64 v190, v190, v97
	v_add_f32_e64 v191, v191, v98
	v_cvt_pk_bf16_f32 v176, v96, v97
	v_cvt_pk_bf16_f32 v177, v98, v99
	v_cvt_pk_bf16_f32 v178, v100, v101
	v_cvt_pk_bf16_f32 v179, v102, v103
	v_add_f32_e64 v196, v196, v99
	v_add_f32_e64 v167, v167, v100
	v_add_f32_e64 v190, v190, v101
	v_add_f32_e64 v191, v191, v102
	v_add_f32_e32 v196, v196, v103
	s_branch .Lat_loop
; #define MFMA(a, b, c) __builtin_amdgcn_mfma_f32_32x32x16_bf16((a), (b), (c), 0, 0, 0)
; DI void attn_item(const P& p, int l, int item, char* smem) {
;     ...
;     if (kt >= 0) {
;       const u16* Kc = Ks + (kt & 1) * (256 * 72);
;       const u16* Vc = Kc + 2 * 64 * 72;
;       bf16x8 kf[8];
; #pragma unroll
;       for (int i = 0; i < 8; ++i)
;         kf[i] = *(const bf16x8*)(Kc + (c * 64 + 32 * (i & 1) + li) * 72 + 16 * (i >> 1) + 8 * g);
;       u32x4 vf[16];
; #pragma unroll
;       for (int i = 0; i < 16; ++i) {
;         const int eb = i & 3, s = (i >> 2) & 1, kb = i >> 3;
;         vf[i] = *(const u32x4*)(Vc + (32 * eb + li) * 72 + 32 * kb + 16 * s + 8 * g);
;       }
;       f32x16 S[2];
; #pragma unroll
;       for (int kb = 0; kb < 2; ++kb)
; #pragma unroll
;         for (int r = 0; r < 16; ++r) S[kb][r] = negm;
; #pragma unroll
;       for (int i = 0; i < 8; ++i) S[i & 1] = MFMA(kf[i], qf[i >> 1], S[i & 1]);
;       u32x4 pk[4];
;       float sum = 0.f;
; #pragma unroll
;       for (int ch = 0; ch < 4; ++ch) {
;         const int kb = ch >> 1, s = ch & 1;
; #pragma unroll
;         for (int j2 = 0; j2 < 4; ++j2) {
;           const float p0 = __builtin_amdgcn_exp2f(S[kb][8 * s + 2 * j2]);
;           const float p1 = __builtin_amdgcn_exp2f(S[kb][8 * s + 2 * j2 + 1]);
;           sum += p0 + p1;
;           pk[ch][j2] = pack2(p0, p1);
;         }
;       }
;       ls += sum;
; #pragma unroll
;       for (int i = 0; i < 16; ++i) {
;         const int eb = i & 3, ch = i >> 2;
;         O[eb] = MFMA(__builtin_bit_cast(bf16x8, vf[i]), __builtin_bit_cast(bf16x8, pk[ch]), O[eb]);
;       }
.Lat_exit:
	global_load_dwordx4 v[232:235], v[148:149], off
	global_load_dwordx4 v[228:231], v[156:157], off
	global_load_dwordx4 v[236:239], v[146:147], off
	global_load_dwordx4 v[240:243], v[144:145], off
	v_add_f32_e64 v167, v167, v190
	v_add_f32_e64 v191, v191, v196
	s_nop 0
	v_add_f32_e64 v167, v167, v191
	v_add_u32_e32 v80, 0xd800, v169
	s_waitcnt vmcnt(2)
	ds_write_b128 v168, v[228:231] offset:36864
	ds_write_b128 v168, v[232:235] offset:46080
	s_waitcnt vmcnt(1)
	ds_write2_b64 v80, v[236:237], v[238:239] offset1:2
	v_add_u32_e32 v80, 0xd800, v143
	s_waitcnt vmcnt(0)
	ds_write2_b64 v80, v[240:241], v[242:243] offset1:2
	v_add3_u32 v129, 0, v175, v188
	ds_read_b128 v[80:83], v129
	ds_read_b128 v[130:133], v129 offset:4608
	v_add3_u32 v128, 0, v174, v188
	ds_read_b128 v[134:137], v128 offset:18432
	v_readlane_b32 s6, v248, 5
	s_waitcnt lgkmcnt(2)
	v_mfma_f32_32x32x16_bf16 v[96:111], v[80:83], v[112:115], v[16:31]
	s_waitcnt lgkmcnt(1)
	v_mfma_f32_32x32x16_bf16 v[80:95], v[130:133], v[112:115], v[16:31]
	ds_read_b128 v[130:133], v129 offset:32
	s_waitcnt lgkmcnt(0)
	v_mfma_f32_32x32x16_bf16 v[96:111], v[130:133], v[116:119], v[96:111]
	ds_read_b128 v[130:133], v129 offset:4640
	s_waitcnt lgkmcnt(0)
	v_mfma_f32_32x32x16_bf16 v[80:95], v[130:133], v[116:119], v[80:95]
	ds_read_b128 v[130:133], v129 offset:64
	s_waitcnt lgkmcnt(0)
	v_mfma_f32_32x32x16_bf16 v[96:111], v[130:133], v[124:127], v[96:111]
	ds_read_b128 v[130:133], v129 offset:4672
	s_waitcnt lgkmcnt(0)
	v_mfma_f32_32x32x16_bf16 v[80:95], v[130:133], v[124:127], v[80:95]
	ds_read_b128 v[130:133], v129 offset:96
	s_waitcnt lgkmcnt(0)
	v_mfma_f32_32x32x16_bf16 v[96:111], v[130:133], v[120:123], v[96:111]
	ds_read_b128 v[130:133], v129 offset:4704
	s_nop 10
	v_exp_f32_e32 v144, v100
	v_exp_f32_e32 v145, v101
	v_exp_f32_e32 v146, v102
	v_exp_f32_e32 v147, v103
	ds_read_b128 v[100:103], v128 offset:23040
	v_exp_f32_e32 v138, v96
	v_exp_f32_e32 v139, v97
	v_exp_f32_e32 v142, v98
	v_exp_f32_e32 v143, v99
	v_cvt_pk_bf16_f32 v98, v144, v145
	v_cvt_pk_bf16_f32 v96, v138, v139
	v_cvt_pk_bf16_f32 v99, v146, v147
	v_cvt_pk_bf16_f32 v97, v142, v143
	v_exp_f32_e32 v108, v108
	v_exp_f32_e32 v109, v109
	s_waitcnt lgkmcnt(0)
	v_mfma_f32_32x32x16_bf16 v[48:63], v[100:103], v[96:99], v[48:63]
	ds_read_b128 v[100:103], v128 offset:27648
	v_exp_f32_e32 v110, v110
	v_exp_f32_e32 v111, v111
	v_mfma_f32_32x32x16_bf16 v[80:95], v[130:133], v[120:123], v[80:95]
	s_waitcnt lgkmcnt(0)
	v_mfma_f32_32x32x16_bf16 v[32:47], v[100:103], v[96:99], v[32:47]
	ds_read_b128 v[100:103], v128 offset:32256
	ds_read_b128 v[130:133], v128 offset:18464
	s_nop 7
	v_exp_f32_e32 v148, v84
	v_exp_f32_e32 v149, v85
	v_exp_f32_e32 v150, v86
	v_exp_f32_e32 v151, v87
	v_exp_f32_e32 v152, v88
	v_exp_f32_e32 v153, v89
	s_waitcnt lgkmcnt(1)
	v_mfma_f32_32x32x16_bf16 v[0:15], v[100:103], v[96:99], v[0:15]
	ds_read_b128 v[100:103], v128 offset:23072
	v_exp_f32_e32 v154, v90
	v_exp_f32_e32 v155, v91
	v_exp_f32_e32 v156, v92
	v_exp_f32_e32 v157, v93
	v_exp_f32_e32 v168, v94
	v_exp_f32_e32 v169, v95
	v_mfma_f32_32x32x16_bf16 v[64:79], v[134:137], v[96:99], v[64:79]
	v_exp_f32_e32 v134, v104
	v_exp_f32_e32 v135, v105
	v_exp_f32_e32 v136, v106
	v_exp_f32_e32 v137, v107
	v_cvt_pk_bf16_f32 v98, v108, v109
	v_cvt_pk_bf16_f32 v96, v134, v135
	v_cvt_pk_bf16_f32 v99, v110, v111
	v_cvt_pk_bf16_f32 v97, v136, v137
	v_add_f32_e32 v88, v165, v166
	v_mul_f32_e32 v165, 0x3fb8aa3b, v88
	s_waitcnt lgkmcnt(0)
	v_mfma_f32_32x32x16_bf16 v[48:63], v[100:103], v[96:99], v[48:63]
	ds_read_b128 v[100:103], v128 offset:27680
	v_add_f32_e32 v134, v134, v135
	s_waitcnt lgkmcnt(0)
	v_mfma_f32_32x32x16_bf16 v[32:47], v[100:103], v[96:99], v[32:47]
	ds_read_b128 v[100:103], v128 offset:32288
	ds_read_b128 v[104:107], v128 offset:18496
	ds_read_b128 v[84:87], v128 offset:23104
	v_mfma_f32_32x32x16_bf16 v[64:79], v[130:133], v[96:99], v[64:79]
	v_exp_f32_e32 v130, v80
	v_exp_f32_e32 v131, v81
	v_exp_f32_e32 v132, v82
	v_exp_f32_e32 v133, v83
	v_cvt_pk_bf16_f32 v82, v148, v149
	v_cvt_pk_bf16_f32 v80, v130, v131
	v_cvt_pk_bf16_f32 v83, v150, v151
	v_cvt_pk_bf16_f32 v81, v132, v133
	s_waitcnt lgkmcnt(2)
	v_mfma_f32_32x32x16_bf16 v[0:15], v[100:103], v[96:99], v[0:15]
	s_waitcnt lgkmcnt(0)
	v_mfma_f32_32x32x16_bf16 v[48:63], v[84:87], v[80:83], v[48:63]
	ds_read_b128 v[84:87], v128 offset:27712
	s_waitcnt lgkmcnt(0)
	v_mfma_f32_32x32x16_bf16 v[32:47], v[84:87], v[80:83], v[32:47]
	ds_read_b128 v[84:87], v128 offset:32320
	ds_read_b128 v[96:99], v128 offset:18528
	s_waitcnt lgkmcnt(1)
	v_mfma_f32_32x32x16_bf16 v[0:15], v[84:87], v[80:83], v[0:15]
	ds_read_b128 v[84:87], v128 offset:23136
	v_mfma_f32_32x32x16_bf16 v[64:79], v[104:107], v[80:83], v[64:79]
	v_cvt_pk_bf16_f32 v80, v152, v153
	v_cvt_pk_bf16_f32 v81, v154, v155
	v_cvt_pk_bf16_f32 v82, v156, v157
	v_cvt_pk_bf16_f32 v83, v168, v169
	s_waitcnt lgkmcnt(0)
	s_nop 0
	v_mfma_f32_32x32x16_bf16 v[48:63], v[84:87], v[80:83], v[48:63]
	ds_read_b128 v[84:87], v128 offset:27744
	s_waitcnt lgkmcnt(0)
	v_mfma_f32_32x32x16_bf16 v[32:47], v[84:87], v[80:83], v[32:47]
	ds_read_b128 v[84:87], v128 offset:32352
	s_waitcnt lgkmcnt(0)
	s_barrier
; #define MFMA(a, b, c) __builtin_amdgcn_mfma_f32_32x32x16_bf16((a), (b), (c), 0, 0, 0)
; DI void attn_item(const P& p, int l, int item, char* smem) {
;     ...
;       for (int i = 0; i < 8; ++i) S[i & 1] = MFMA(kf[i], qf[i >> 1], S[i & 1]);
;       u32x4 pk[4];
;       float sum = 0.f;
; #pragma unroll
;       for (int ch = 0; ch < 4; ++ch) {
;         const int kb = ch >> 1, s = ch & 1;
; #pragma unroll
;         for (int j2 = 0; j2 < 4; ++j2) {
;           const float p0 = __builtin_amdgcn_exp2f(S[kb][8 * s + 2 * j2]);
;           const float p1 = __builtin_amdgcn_exp2f(S[kb][8 * s + 2 * j2 + 1]);
;           sum += p0 + p1;
;           pk[ch][j2] = pack2(p0, p1);
;         }
;       }
;       ls += sum;
; #pragma unroll
;       for (int i = 0; i < 16; ++i) {
;         const int eb = i & 3, ch = i >> 2;
;         O[eb] = MFMA(__builtin_bit_cast(bf16x8, vf[i]), __builtin_bit_cast(bf16x8, pk[ch]), O[eb]);
	v_mfma_f32_32x32x16_bf16 v[64:79], v[96:99], v[80:83], v[64:79]
	ds_read_b128 v[96:99], v129 offset:36864
	ds_read_b128 v[100:103], v129 offset:41472
	ds_read_b128 v[104:107], v129 offset:36896
	v_mfma_f32_32x32x16_bf16 v[0:15], v[84:87], v[80:83], v[0:15]
	v_add_f32_e32 v80, v138, v139
	v_add_f32_e32 v80, 0, v80
	v_add_f32_e32 v81, v142, v143
	v_add_f32_e32 v138, v81, v80
	v_exp_f32_e32 v139, v165
	s_waitcnt lgkmcnt(2)
	v_mfma_f32_32x32x16_bf16 v[80:95], v[96:99], v[112:115], v[16:31]
	v_add_f32_e32 v96, v144, v145
	v_add_f32_e32 v96, v96, v138
	v_add_f32_e32 v97, v146, v147
	v_add_f32_e32 v138, v97, v96
	v_add_f32_e32 v134, v134, v138
	ds_read_b128 v[96:99], v129 offset:41504
	s_waitcnt lgkmcnt(2)
	v_mfma_f32_32x32x16_bf16 v[16:31], v[100:103], v[112:115], v[16:31]
	v_add_f32_e32 v100, v136, v137
	v_add_f32_e32 v100, v100, v134
	v_add_f32_e32 v101, v108, v109
	v_add_f32_e32 v100, v101, v100
	v_add_f32_e32 v101, v110, v111
	v_add_f32_e32 v100, v101, v100
	v_add_f32_e32 v101, v130, v131
	v_add_f32_e32 v100, v101, v100
	v_add_f32_e32 v101, v132, v133
	s_waitcnt lgkmcnt(1)
	v_mfma_f32_32x32x16_bf16 v[80:95], v[104:107], v[116:119], v[80:95]
	v_add_f32_e32 v104, v101, v100
	ds_read_b128 v[100:103], v129 offset:36928
	v_add_f32_e32 v105, v148, v149
	v_add_f32_e32 v104, v105, v104
	v_add_f32_e32 v105, v150, v151
	v_add_f32_e32 v108, v105, v104
	v_add_f32_e32 v109, v152, v153
	s_waitcnt lgkmcnt(0)
	v_mfma_f32_32x32x16_bf16 v[80:95], v[100:103], v[124:127], v[80:95]
	v_add_f32_e32 v110, v154, v155
	v_add_f32_e32 v100, v109, v108
	v_add_f32_e32 v111, v156, v157
	v_add_f32_e32 v100, v110, v100
	v_add_f32_e32 v112, v168, v169
	v_add_f32_e32 v100, v111, v100
	v_add_f32_e32 v108, v112, v100
	v_mfma_f32_32x32x16_bf16 v[16:31], v[96:99], v[116:119], v[16:31]
	ds_read_b128 v[96:99], v129 offset:41536
	ds_read_b128 v[104:107], v129 offset:36960
	ds_read_b128 v[100:103], v129 offset:41568
	v_add_f32_e32 v129, v167, v108
	v_add_f32_e32 v108, v163, v164
	v_mul_f32_e32 v138, 0x3fb8aa3b, v108
	v_add_u32_e32 v150, 0xd800, v128
	s_waitcnt lgkmcnt(1)
	v_mfma_f32_32x32x16_bf16 v[80:95], v[104:107], v[120:123], v[80:95]
	v_mfma_f32_32x32x16_bf16 v[16:31], v[96:99], v[124:127], v[16:31]
	s_nop 10
	v_exp_f32_e32 v154, v80
	v_exp_f32_e32 v155, v81
	v_exp_f32_e32 v156, v82
	v_exp_f32_e32 v157, v83
	v_exp_f32_e32 v163, v84
	v_exp_f32_e32 v164, v85
	v_exp_f32_e32 v165, v86
	v_exp_f32_e32 v166, v87
	ds_read_b128 v[96:99], v128 offset:55296
	ds_read_b128 v[108:111], v128 offset:55328
	ds_read_b128 v[112:115], v128 offset:59904
	ds_read_b128 v[116:119], v128 offset:59936
	s_waitcnt lgkmcnt(4)
	v_mfma_f32_32x32x16_bf16 v[16:31], v[100:103], v[120:123], v[16:31]
	ds_read_b128 v[84:87], v128 offset:64512
	ds_read_b128 v[100:103], v128 offset:64544
	v_cvt_pk_bf16_f32 v80, v154, v155
	v_cvt_pk_bf16_f32 v81, v156, v157
	v_cvt_pk_bf16_f32 v82, v163, v164
	v_cvt_pk_bf16_f32 v83, v165, v166
	s_nop 5
	v_exp_f32_e32 v16, v16
	s_waitcnt lgkmcnt(5)
	v_mfma_f32_32x32x16_bf16 v[64:79], v[96:99], v[80:83], v[64:79]
	ds_read_b128 v[96:99], v150 offset:13824
	ds_read_b128 v[104:107], v150 offset:13856
	ds_read_b128 v[120:123], v128 offset:55360
	ds_read_b128 v[124:127], v128 offset:55392
	ds_read_b128 v[130:133], v128 offset:59968
	ds_read_b128 v[134:137], v128 offset:60000
	ds_read_b128 v[142:145], v128 offset:64576
	v_exp_f32_e32 v17, v17
	v_exp_f32_e32 v18, v18
	v_exp_f32_e32 v19, v19
	v_exp_f32_e32 v20, v20
	v_exp_f32_e32 v21, v21
	v_exp_f32_e32 v22, v22
	s_waitcnt lgkmcnt(10)
	v_mfma_f32_32x32x16_bf16 v[48:63], v[112:115], v[80:83], v[48:63]
	ds_read_b128 v[112:115], v128 offset:64608
	ds_read_b128 v[146:149], v150 offset:13888
	ds_read_b128 v[150:153], v150 offset:13920
	v_add_f32_e32 v128, v154, v155
	v_add_f32_e32 v128, 0, v128
	v_add_f32_e32 v154, v156, v157
	v_add_f32_e32 v128, v154, v128
	v_exp_f32_e32 v23, v23
	s_waitcnt lgkmcnt(0)
	v_mfma_f32_32x32x16_bf16 v[32:47], v[84:87], v[80:83], v[32:47]
	v_exp_f32_e32 v85, v88
	v_exp_f32_e32 v86, v89
	v_exp_f32_e32 v87, v90
	v_exp_f32_e32 v88, v91
	v_add_f32_e32 v84, v163, v164
	v_exp_f32_e32 v89, v92
	v_exp_f32_e32 v90, v93
	v_add_f32_e32 v84, v84, v128
	v_mfma_f32_32x32x16_bf16 v[0:15], v[96:99], v[80:83], v[0:15]
	v_exp_f32_e32 v91, v94
	v_exp_f32_e32 v92, v95
	v_add_f32_e32 v93, v165, v166
	v_cvt_pk_bf16_f32 v80, v85, v86
	v_add_f32_e32 v84, v93, v84
	v_add_f32_e32 v85, v85, v86
	v_add_f32_e32 v84, v85, v84
	v_add_f32_e32 v85, v87, v88
	v_add_f32_e32 v84, v85, v84
	v_add_f32_e32 v85, v89, v90
	v_add_f32_e32 v84, v85, v84
	v_add_f32_e32 v85, v91, v92
	v_add_f32_e32 v84, v85, v84
	v_add_f32_e32 v85, v16, v17
	v_add_f32_e32 v84, v85, v84
	v_cvt_pk_bf16_f32 v16, v16, v17
	v_add_f32_e32 v17, v18, v19
	v_cvt_pk_bf16_f32 v81, v87, v88
	v_cvt_pk_bf16_f32 v82, v89, v90
	v_cvt_pk_bf16_f32 v83, v91, v92
	v_add_f32_e32 v84, v17, v84
	v_cvt_pk_bf16_f32 v17, v18, v19
	v_add_f32_e32 v18, v20, v21
	v_mfma_f32_32x32x16_bf16 v[64:79], v[108:111], v[80:83], v[64:79]
	v_cvt_pk_bf16_f32 v19, v22, v23
	s_barrier
; #define MFMA(a, b, c) __builtin_amdgcn_mfma_f32_32x32x16_bf16((a), (b), (c), 0, 0, 0)
; DI void attn_item(const P& p, int l, int item, char* smem) {
;     ...
;       ls += sum;
; #pragma unroll
;       for (int i = 0; i < 16; ++i) {
;         const int eb = i & 3, ch = i >> 2;
;         O[eb] = MFMA(__builtin_bit_cast(bf16x8, vf[i]), __builtin_bit_cast(bf16x8, pk[ch]), O[eb]);
;       }
;     }
;     __syncthreads();
;   }
;   const float lt = ls + __shfl_xor(ls, 32);
;   const float inv = (c == 0) ? (1.0f / lt) : (lam / lt);
;   float* exch = (float*)smem + qg * (64 * 64);
;   if (c == 1) {
; #pragma unroll
;     for (int eb = 0; eb < 4; ++eb)
; #pragma unroll
;       for (int r = 0; r < 16; ++r) exch[(eb * 16 + r) * 64 + lane] = O[eb][r] * inv;
;   }
	v_mfma_f32_32x32x16_bf16 v[48:63], v[116:119], v[80:83], v[48:63]
	v_mfma_f32_32x32x16_bf16 v[32:47], v[100:103], v[80:83], v[32:47]
	v_mfma_f32_32x32x16_bf16 v[0:15], v[104:107], v[80:83], v[0:15]
	v_add_f32_e32 v80, v18, v84
	v_cvt_pk_bf16_f32 v18, v20, v21
	v_add_f32_e32 v20, v22, v23
	v_exp_f32_e32 v21, v24
	v_exp_f32_e32 v22, v25
	v_exp_f32_e32 v23, v26
	v_exp_f32_e32 v25, v27
	v_add_f32_e32 v24, v20, v80
	v_add_f32_e32 v26, v21, v22
	v_cvt_pk_bf16_f32 v20, v21, v22
	v_add_f32_e32 v27, v23, v25
	v_cvt_pk_bf16_f32 v21, v23, v25
	v_exp_f32_e32 v22, v28
	v_exp_f32_e32 v23, v29
	v_exp_f32_e32 v25, v30
	v_exp_f32_e32 v28, v31
	v_add_f32_e32 v24, v26, v24
	v_add_f32_e32 v29, v22, v23
	v_add_f32_e32 v24, v27, v24
	v_add_f32_e32 v30, v25, v28
	v_add_f32_e32 v24, v29, v24
	v_mfma_f32_32x32x16_bf16 v[64:79], v[120:123], v[16:19], v[64:79]
	v_cvt_pk_bf16_f32 v22, v22, v23
	v_cvt_pk_bf16_f32 v23, v25, v28
	v_mfma_f32_32x32x16_bf16 v[48:63], v[130:133], v[16:19], v[48:63]
	v_mfma_f32_32x32x16_bf16 v[32:47], v[142:145], v[16:19], v[32:47]
	v_mfma_f32_32x32x16_bf16 v[0:15], v[146:149], v[16:19], v[0:15]
	v_add_f32_e32 v16, v30, v24
	v_exp_f32_e32 v17, v138
	v_add_f32_e32 v16, v129, v16
	ds_bpermute_b32 v18, v158, v16
	v_sub_f32_e32 v17, v17, v139
	v_add_f32_e32 v17, s6, v17
	s_movk_i32 s6, 0x100
	v_cmp_gt_u32_e64 s[6:7], s6, v161
	s_waitcnt lgkmcnt(0)
	v_add_f32_e32 v16, v16, v18
	v_mfma_f32_32x32x16_bf16 v[64:79], v[124:127], v[20:23], v[64:79]
	v_cndmask_b32_e64 v17, v17, 1.0, s[6:7]
	v_div_scale_f32 v18, s[10:11], v16, v16, v17
	v_rcp_f32_e32 v19, v18
	s_nop 0
	v_fma_f32 v24, -v18, v19, 1.0
	v_mfma_f32_32x32x16_bf16 v[48:63], v[134:137], v[20:23], v[48:63]
	v_fmac_f32_e32 v19, v24, v19
	v_div_scale_f32 v24, vcc, v17, v16, v17
	v_mul_f32_e32 v25, v24, v19
	v_fma_f32 v26, -v18, v25, v24
	v_fmac_f32_e32 v25, v26, v19
	v_fma_f32 v18, -v18, v25, v24
	v_mfma_f32_32x32x16_bf16 v[32:47], v[112:115], v[20:23], v[32:47]
	v_div_fmas_f32 v18, v18, v19, v25
	v_div_fixup_f32 v80, v18, v16, v17
	v_lshl_add_u32 v16, v162, 14, 0
	v_cmp_eq_u32_e32 vcc, 1, v160
	v_lshl_add_u32 v18, v141, 2, v16
	v_mfma_f32_32x32x16_bf16 v[0:15], v[150:153], v[20:23], v[0:15]
	s_and_saveexec_b64 s[10:11], vcc
	s_cbranch_execz .LBB0_469
	v_mul_f32_e32 v16, v64, v80
	v_mul_f32_e32 v17, v65, v80
	ds_write2st64_b32 v18, v16, v17 offset1:1
	v_mul_f32_e32 v16, v66, v80
	v_mul_f32_e32 v17, v67, v80
	ds_write2st64_b32 v18, v16, v17 offset0:2 offset1:3
	v_mul_f32_e32 v16, v68, v80
	v_mul_f32_e32 v17, v69, v80
	ds_write2st64_b32 v18, v16, v17 offset0:4 offset1:5
	v_mul_f32_e32 v16, v70, v80
	v_mul_f32_e32 v17, v71, v80
	ds_write2st64_b32 v18, v16, v17 offset0:6 offset1:7
	v_mul_f32_e32 v16, v72, v80
	v_mul_f32_e32 v17, v73, v80
	ds_write2st64_b32 v18, v16, v17 offset0:8 offset1:9
	v_mul_f32_e32 v16, v74, v80
	v_mul_f32_e32 v17, v75, v80
	ds_write2st64_b32 v18, v16, v17 offset0:10 offset1:11
	v_mul_f32_e32 v16, v76, v80
	v_mul_f32_e32 v17, v77, v80
	ds_write2st64_b32 v18, v16, v17 offset0:12 offset1:13
	v_mul_f32_e32 v16, v78, v80
	v_mul_f32_e32 v17, v79, v80
	ds_write2st64_b32 v18, v16, v17 offset0:14 offset1:15
	v_mul_f32_e32 v16, v48, v80
	v_mul_f32_e32 v17, v49, v80
	ds_write2st64_b32 v18, v16, v17 offset0:16 offset1:17
	v_mul_f32_e32 v16, v50, v80
	v_mul_f32_e32 v17, v51, v80
	ds_write2st64_b32 v18, v16, v17 offset0:18 offset1:19
	v_mul_f32_e32 v16, v52, v80
	v_mul_f32_e32 v17, v53, v80
	ds_write2st64_b32 v18, v16, v17 offset0:20 offset1:21
	v_mul_f32_e32 v16, v54, v80
	v_mul_f32_e32 v17, v55, v80
	ds_write2st64_b32 v18, v16, v17 offset0:22 offset1:23
	v_mul_f32_e32 v16, v56, v80
	v_mul_f32_e32 v17, v57, v80
	ds_write2st64_b32 v18, v16, v17 offset0:24 offset1:25
	v_mul_f32_e32 v16, v58, v80
	v_mul_f32_e32 v17, v59, v80
	ds_write2st64_b32 v18, v16, v17 offset0:26 offset1:27
	v_mul_f32_e32 v16, v60, v80
	v_mul_f32_e32 v17, v61, v80
	ds_write2st64_b32 v18, v16, v17 offset0:28 offset1:29
	v_mul_f32_e32 v16, v62, v80
	v_mul_f32_e32 v17, v63, v80
	ds_write2st64_b32 v18, v16, v17 offset0:30 offset1:31
	v_mul_f32_e32 v16, v32, v80
	v_mul_f32_e32 v17, v33, v80
	ds_write2st64_b32 v18, v16, v17 offset0:32 offset1:33
	v_mul_f32_e32 v16, v34, v80
	v_mul_f32_e32 v17, v35, v80
	ds_write2st64_b32 v18, v16, v17 offset0:34 offset1:35
	v_mul_f32_e32 v16, v36, v80
	v_mul_f32_e32 v17, v37, v80
	ds_write2st64_b32 v18, v16, v17 offset0:36 offset1:37
	v_mul_f32_e32 v16, v38, v80
	v_mul_f32_e32 v17, v39, v80
	ds_write2st64_b32 v18, v16, v17 offset0:38 offset1:39
	v_mul_f32_e32 v16, v40, v80
	v_mul_f32_e32 v17, v41, v80
	ds_write2st64_b32 v18, v16, v17 offset0:40 offset1:41
	v_mul_f32_e32 v16, v42, v80
	v_mul_f32_e32 v17, v43, v80
	ds_write2st64_b32 v18, v16, v17 offset0:42 offset1:43
	v_mul_f32_e32 v16, v44, v80
	v_mul_f32_e32 v17, v45, v80
	ds_write2st64_b32 v18, v16, v17 offset0:44 offset1:45
	v_mul_f32_e32 v16, v46, v80
	v_mul_f32_e32 v17, v47, v80
	ds_write2st64_b32 v18, v16, v17 offset0:46 offset1:47
	v_mul_f32_e32 v16, v0, v80
	v_mul_f32_e32 v17, v1, v80
	ds_write2st64_b32 v18, v16, v17 offset0:48 offset1:49
	v_mul_f32_e32 v16, v2, v80
	v_mul_f32_e32 v17, v3, v80
	ds_write2st64_b32 v18, v16, v17 offset0:50 offset1:51
	v_mul_f32_e32 v16, v4, v80
	v_mul_f32_e32 v17, v5, v80
	ds_write2st64_b32 v18, v16, v17 offset0:52 offset1:53
	v_mul_f32_e32 v16, v6, v80
	v_mul_f32_e32 v17, v7, v80
	ds_write2st64_b32 v18, v16, v17 offset0:54 offset1:55
	v_mul_f32_e32 v16, v8, v80
	v_mul_f32_e32 v17, v9, v80
	ds_write2st64_b32 v18, v16, v17 offset0:56 offset1:57
	v_mul_f32_e32 v16, v10, v80
	v_mul_f32_e32 v17, v11, v80
	ds_write2st64_b32 v18, v16, v17 offset0:58 offset1:59
	v_mul_f32_e32 v16, v12, v80
	v_mul_f32_e32 v17, v13, v80
	ds_write2st64_b32 v18, v16, v17 offset0:60 offset1:61
	v_mul_f32_e32 v16, v14, v80
	v_mul_f32_e32 v17, v15, v80
	ds_write2st64_b32 v18, v16, v17 offset0:62 offset1:63
